# plus: LRU per-workgroup constant tables filled once per pass instead of per item
# speedup vs baseline: 1.0136x; 1.0007x over previous
;     __device__ __forceinline__ const float* in(int k) const { return (const float*)(const __attribute__((address_space(1))) float*)rd(k); }
; template <int pass>
; __device__ __forceinline__ void lru_item(const Ctx& a, LAS unsigned char* lds, int l, int b, int n, int seg, const int tid) {
;     ...
;     if (tid < 320) CWs[tid] = tid < 256 ? cw[(tid >> 6) * 512 + (tid & 63)] : cbias[tid - 256];
;     if (tid >= 384) { const int d = (tid - 384) >> 6, chl = tid & 63, ch = (l * 2 + d) * 512 + cb + chl;
;         const float lam = a.in(17)[ch];
;         CPs[d * 192 + chl] = -1.4426950408889634f * a.in(14)[ch]; CPs[d * 192 + 64 + chl] = -1.4426950408889634f * a.in(16)[ch];
;         CPs[d * 192 + 128 + chl] = -8.0f * 1.4426950408889634f * ((lam > 15.f) ? __expf(-lam) : log1pf(__expf(-lam))); }
.LBB0_369:
	s_or_b64 exec, exec, s[14:15]
	v_readlane_b32 s6, v246, 62
	s_nop 0
	s_cmp_lg_u32 s86, s6
	s_cbranch_scc1 .Llru1_cdone
	s_movk_i32 s6, 0x140
	v_cmp_gt_i32_e32 vcc, s6, v56
	s_and_saveexec_b64 s[6:7], vcc
	s_cbranch_execz .LBB0_375
	s_movk_i32 s10, 0xff
	v_cmp_lt_i32_e32 vcc, s10, v56
	s_and_saveexec_b64 s[14:15], vcc
	s_xor_b64 s[14:15], exec, s[14:15]
	s_cbranch_execz .LBB0_372
	v_readlane_b32 s10, v244, 32
	v_readlane_b32 s11, v244, 33
	s_add_u32 s10, s36, s10
	s_addc_u32 s11, s35, s11
	s_lshl_b32 s18, s77, 2
	s_add_u32 s18, s10, s18
	s_addc_u32 s19, s11, 0
	v_mov_b32_e32 v57, v1
	s_movk_i32 s10, 0xfc00
	v_lshl_add_u64 v[2:3], v[56:57], 2, s[18:19]
	s_mov_b32 s11, -1
	v_lshl_add_u64 v[2:3], v[2:3], 0, s[10:11]

; #define LAS __attribute__((address_space(3)))
; template <int pass>
; __device__ __forceinline__ void lru_item(const Ctx& a, LAS unsigned char* lds, int l, int b, int n, int seg, const int tid) {
;     ...
;         for (int i = 0; i < 2; ++i) { const int v = tid + 512 * i, mat = v >> 9, row = (v >> 3) & 63, c8 = v & 7; *(LAS u32x4*)(WLs + mat * 9216 + row * 144 + c8 * 16) = wpre[i]; }
;         if (pass == 1) *(LAS f32x4*)(AGs + 4 * tid) = agpre;
;         float ba[4], bi[4], sp[4], hin[4], ain[4];
; #pragma unroll
;         for (int nt = 0; nt < 4; ++nt) { hin[nt] = 0.f; ain[nt] = 1.f; }
;         __syncthreads();
; #pragma unroll
;         for (int nt = 0; nt < 4; ++nt) { ba[nt] = CPs[dir * 192 + 16 * nt + c15]; bi[nt] = CPs[dir * 192 + 64 + 16 * nt + c15]; sp[nt] = CPs[dir * 192 + 128 + 16 * nt + c15]; }
;         if (pass == 1) {
; #pragma unroll
;             for (int nt = 0; nt < 4; ++nt) { float h0 = 0.f;
;                 if (dir == 0) { for (int s2 = 0; s2 < seg; ++s2) { const LAS float* q = AGs + s2 * 128 + (16 * nt + c15) * 2; h0 = q[0] * h0 + q[1]; } }
.Llru1_cdone:
	v_bfe_u32 v0, v56, 3, 6
	v_lshlrev_b32_e32 v2, 4, v56
	v_mul_u32_u24_e32 v0, 0x90, v0
	v_and_b32_e32 v3, 0x70, v2
	v_readlane_b32 s6, v245, 22
	v_and_b32_e32 v122, 15, v56
	v_lshl_add_u32 v142, v122, 2, 0
	v_add3_u32 v140, s6, v0, v3
	v_add_u32_e32 v0, 0, v2
	s_movk_i32 s6, 0x2400
	v_add_u32_e32 v141, 0x1e600, v0
	v_mad_i32_i24 v0, v58, s6, v140
	s_waitcnt vmcnt(0)
	ds_write_b128 v0, v[36:39]
	v_mad_i32_i24 v0, v60, s6, v140
	ds_write_b128 v0, v[40:43]
	ds_write_b128 v141, v[44:47]
	v_add_u32_e32 v0, 0x20b00, v142
	s_waitcnt lgkmcnt(0)
	s_barrier
	v_add_u32_e32 v2, 0x20c00, v142
	v_add_u32_e32 v3, 0x20d00, v142
	ds_read2_b32 v[62:63], v0 offset1:16
	ds_read2_b32 v[64:65], v2 offset1:16
	ds_read2_b32 v[66:67], v3 offset1:16
	ds_read2_b32 v[68:69], v0 offset0:32 offset1:48
	ds_read2_b32 v[70:71], v2 offset0:32 offset1:48
	ds_read2_b32 v[72:73], v3 offset0:32 offset1:48
	s_cmp_lt_i32 s88, 15
	s_cselect_b64 s[6:7], -1, 0
	v_lshlrev_b32_e32 v138, 3, v122
	v_cndmask_b32_e64 v0, 0, 1, s[6:7]
	v_mul_i32_i24_e32 v144, 0x2400, v58
	v_mul_i32_i24_e32 v143, 0x2400, v60
	v_cmp_ne_u32_e64 s[40:41], 1, v0
	v_mov_b32_e32 v3, 0
	v_mov_b32_e32 v75, 0
	v_mov_b32_e32 v101, 0
	v_mov_b32_e32 v99, 0
	s_cmp_gt_i32 s88, 14
	s_cbranch_scc1 .Llru_bwc_done
	v_readlane_b32 s10, v245, 23
	s_nop 1
	v_add3_u32 v228, s10, v138, -4
	v_readlane_b32 s10, v245, 24
	s_nop 1
	v_add3_u32 v229, s10, v138, -4
	v_readlane_b32 s10, v245, 25
	s_nop 1
	v_add3_u32 v230, s10, v138, -4
	v_readlane_b32 s10, v245, 26
	s_nop 1
	v_add3_u32 v231, s10, v138, -4
	s_mov_b32 s14, 15

;     __device__ __forceinline__ const float* in(int k) const { return (const float*)(const __attribute__((address_space(1))) float*)rd(k); }
; template <int pass>
; __device__ __forceinline__ void lru_item(const Ctx& a, LAS unsigned char* lds, int l, int b, int n, int seg, const int tid) {
;     ...
;     if (tid < 320) CWs[tid] = tid < 256 ? cw[(tid >> 6) * 512 + (tid & 63)] : cbias[tid - 256];
;     if (tid >= 384) { const int d = (tid - 384) >> 6, chl = tid & 63, ch = (l * 2 + d) * 512 + cb + chl;
;         const float lam = a.in(17)[ch];
;         CPs[d * 192 + chl] = -1.4426950408889634f * a.in(14)[ch]; CPs[d * 192 + 64 + chl] = -1.4426950408889634f * a.in(16)[ch];
;         CPs[d * 192 + 128 + chl] = -8.0f * 1.4426950408889634f * ((lam > 15.f) ? __expf(-lam) : log1pf(__expf(-lam))); }
.LBB0_536:
	s_or_b64 exec, exec, s[6:7]
	v_readlane_b32 s2, v246, 62
	s_nop 0
	s_cmp_lg_u32 s86, s2
	s_cbranch_scc1 .Llru0_cdone
	s_movk_i32 s2, 0x140
	v_cmp_gt_i32_e32 vcc, s2, v56
	s_and_saveexec_b64 s[2:3], vcc
	s_cbranch_execz .LBB0_542
	s_movk_i32 s6, 0xff
	v_cmp_lt_i32_e32 vcc, s6, v56
	s_and_saveexec_b64 s[6:7], vcc
	s_xor_b64 s[6:7], exec, s[6:7]
	s_cbranch_execz .LBB0_539
	v_readlane_b32 s10, v244, 32
	v_readlane_b32 s11, v244, 33
	s_add_u32 s10, s36, s10
	s_addc_u32 s11, s35, s11
	s_lshl_b32 s14, s16, 2
	s_add_u32 s14, s10, s14
	s_addc_u32 s15, s11, 0
	v_mov_b32_e32 v57, v1
	s_movk_i32 s10, 0xfc00
	v_lshl_add_u64 v[2:3], v[56:57], 2, s[14:15]
	s_mov_b32 s11, -1
	v_lshl_add_u64 v[2:3], v[2:3], 0, s[10:11]

; #define LAS __attribute__((address_space(3)))
; __device__ __forceinline__ float bflo(unsigned w) { return __uint_as_float(w << 16); }
; template <int pass>
; __device__ __forceinline__ void lru_item(const Ctx& a, LAS unsigned char* lds, int l, int b, int n, int seg, const int tid) {
;     ...
;         for (int i = 0; i < 2; ++i) { const int v = tid + 512 * i, mat = v >> 9, row = (v >> 3) & 63, c8 = v & 7; *(LAS u32x4*)(WLs + mat * 9216 + row * 144 + c8 * 16) = wpre[i]; }
;         if (pass == 1) *(LAS f32x4*)(AGs + 4 * tid) = agpre;
;         float ba[4], bi[4], sp[4], hin[4], ain[4];
; #pragma unroll
;         for (int nt = 0; nt < 4; ++nt) { hin[nt] = 0.f; ain[nt] = 1.f; }
;         __syncthreads();
; #pragma unroll
;         for (int nt = 0; nt < 4; ++nt) { ba[nt] = CPs[dir * 192 + 16 * nt + c15]; bi[nt] = CPs[dir * 192 + 64 + 16 * nt + c15]; sp[nt] = CPs[dir * 192 + 128 + 16 * nt + c15]; }
;         if (pass == 1) {
; #pragma unroll
;             for (int nt = 0; nt < 4; ++nt) { float h0 = 0.f;
;                 if (dir == 0) { for (int s2 = 0; s2 < seg; ++s2) { const LAS float* q = AGs + s2 * 128 + (16 * nt + c15) * 2; h0 = q[0] * h0 + q[1]; } }
;     ...
;                 hin[nt] = h0; }
;         }
;         for (int c = 0; c < LSEG / 128; ++c) {
;             const int tl0 = dir ? LSEG - 128 * (c + 1) : 128 * c;
; #pragma unroll
;             for (int rep = 0; rep < 2; ++rep) {
;                 const int tokl = (tid + 512 * rep) >> 3, i = dir ? 127 - tokl : tokl;
;                 f32x4 o0 = *(const LAS f32x4*)(CWs + 256 + 8 * cg8), o1 = *(const LAS f32x4*)(CWs + 256 + 8 * cg8 + 4);
; #pragma unroll
;                 for (int tap = 0; tap < 4; ++tap) {
;                     const u32x4 xv = xr[rep][tap];
;                     const f32x4 w0 = *(const LAS f32x4*)(CWs + tap * 64 + 8 * cg8), w1 = *(const LAS f32x4*)(CWs + tap * 64 + 8 * cg8 + 4);
;                     o0[0] += bflo(xv.x) * w0[0]; o0[1] += bfhi(xv.x) * w0[1]; o0[2] += bflo(xv.y) * w0[2]; o0[3] += bfhi(xv.y) * w0[3];
;                     o1[0] += bflo(xv.z) * w1[0]; o1[1] += bfhi(xv.z) * w1[1]; o1[2] += bflo(xv.w) * w1[2]; o1[3] += bfhi(xv.w) * w1[3];
;                 }
;                 *(LAS f32x4*)(XC + i * 68 + 8 * cg8) = o0;
;                 *(LAS f32x4*)(XC + i * 68 + 8 * cg8 + 4) = o1;
;             }
;             if (c + 1 < LSEG / 128) load_x(dir, c + 1);
;             bf16_t gq[4][4];
.Llru0_cdone:
	v_bfe_u32 v2, v56, 3, 6
	v_lshlrev_b32_e32 v3, 4, v56
	v_mul_u32_u24_e32 v2, 0x90, v2
	v_and_b32_e32 v3, 0x70, v3
	v_readlane_b32 s3, v245, 22
	v_bfe_u32 v0, v56, 4, 2
	s_movk_i32 s2, 0x2400
	v_add3_u32 v57, s3, v2, v3
	v_lshlrev_b32_e32 v2, 5, v105
	v_add_u32_e32 v99, 0, v2
	v_ashrrev_i32_e32 v2, 2, v56
	v_and_b32_e32 v3, -16, v2
	v_and_b32_e32 v106, 15, v56
	v_lshlrev_b32_e32 v53, 5, v0
	v_lshlrev_b32_e32 v55, 4, v0
	v_lshl_or_b32 v3, v0, 2, v3
	v_cmp_eq_u32_e64 s[40:41], 0, v0
	v_cmp_eq_u32_e64 s[42:43], 3, v0
	v_mad_i32_i24 v0, v58, s2, v57
	v_lshl_add_u32 v100, v106, 2, 0
	v_add_u32_e32 v45, -16, v169
	v_and_b32_e32 v47, 64, v169
	s_waitcnt vmcnt(0)
	ds_write_b128 v0, v[40:43]
	v_mad_i32_i24 v0, v60, s2, v57
	v_cmp_lt_i32_e32 vcc, v45, v47
	ds_write_b128 v0, v[36:39]
	v_add_u32_e32 v0, 0x20b00, v100
	v_add_u32_e32 v37, 0x20d00, v100
	v_readlane_b32 s6, v245, 27
	v_cndmask_b32_e32 v45, v45, v169, vcc
	s_waitcnt lgkmcnt(0)
	s_barrier
	v_add_u32_e32 v36, 0x20c00, v100
	ds_read2_b32 v[72:73], v0 offset1:16
	ds_read2_b32 v[70:71], v36 offset1:16
	ds_read2_b32 v[68:69], v37 offset1:16
	ds_read2_b32 v[66:67], v0 offset0:32 offset1:48
	ds_read2_b32 v[64:65], v36 offset0:32 offset1:48
	ds_read2_b32 v[62:63], v37 offset0:32 offset1:48
	v_mov_b32_e32 v37, s3
	s_movk_i32 s2, 0x90
	v_mov_b32_e32 v38, s6
	v_lshlrev_b32_e32 v75, 2, v45
	v_subrev_u32_e32 v45, 32, v169
	v_mad_u32_u24 v37, v106, s2, v37
	v_mad_u32_u24 v38, v106, s2, v38
	v_mad_u32_u24 v108, v106, s2, v174
	v_mad_u32_u24 v111, v106, s2, v175
	v_mad_u32_u24 v112, v106, s2, v176
	s_lshl_b32 s2, s86, 9
	v_cmp_lt_i32_e32 vcc, v45, v47
	v_mul_i32_i24_e32 v101, 0x2400, v58
	v_add_u32_e32 v39, s3, v108
	v_add_u32_e32 v40, s6, v108
	v_add_u32_e32 v109, s3, v55
	v_add_u32_e32 v110, s6, v55
	v_add_u32_e32 v41, s3, v111
	v_add_u32_e32 v42, s6, v111
	v_add_u32_e32 v43, s3, v112
	v_add_u32_e32 v58, s6, v112
	v_add_u32_e32 v47, s2, v98
	s_lshl_b32 s3, s84, 13
	s_mul_i32 s6, s87, 0x3000000
	s_mul_i32 s7, s86, 0x300000
	v_subrev_u32_e32 v113, s3, v47
	s_add_i32 s6, s6, s7
	v_mul_lo_u32 v47, v98, s23
	v_add_u32_e32 v47, s6, v47
	s_lshl_b32 s7, s20, 7
	v_or_b32_e32 v47, s7, v47
	v_subrev_u32_e32 v86, s89, v47
	v_add_u32_e32 v47, s2, v103
	v_subrev_u32_e32 v114, s3, v47
	v_mul_lo_u32 v47, v103, s23
	v_bfi_b32 v2, -16, v2, v56
	v_add_u32_e32 v47, s6, v47
	v_mul_lo_u32 v2, v2, s92
	v_sub_u32_e32 v0, 0x7f, v103
	v_sub_u32_e32 v36, 0x7f, v98
	v_or_b32_e32 v47, s7, v47
	v_add_u32_e32 v2, 0, v2
	v_cndmask_b32_e32 v45, v45, v169, vcc
	v_mul_lo_u32 v0, v0, s92
	v_mul_lo_u32 v36, v36, s92
	v_mul_lo_u32 v3, v3, s92
	v_subrev_u32_e32 v87, s89, v47
	v_mov_b32_e32 v52, 1.0
	v_mov_b32_e32 v54, 0
	s_mov_b32 s34, 0
	v_lshlrev_b32_e32 v74, 2, v45
	v_mul_i32_i24_e32 v105, 0x2400, v60
	v_lshl_add_u32 v107, v106, 3, 0
	v_and_b32_e32 v45, 0xfffffe78, v104
	v_add_u32_e32 v104, v99, v0
	v_add_u32_e32 v47, v99, v36
	v_add_u32_e32 v85, v2, v53
	v_add_u32_e32 v84, v37, v55
	v_add_u32_e32 v83, v38, v55
	v_add_u32_e32 v76, v100, v3
	v_add_u32_e32 v82, v39, v55
	v_add_u32_e32 v81, v40, v55
	v_add_u32_e32 v80, v41, v55
	v_add_u32_e32 v79, v42, v55
	v_add_u32_e32 v78, v43, v55
	v_add_u32_e32 v77, v58, v55
	v_mov_b32_e32 v115, v87
	v_mov_b32_e32 v116, v86
	v_mov_b32_e32 v55, v54
	v_mov_b32_e32 v58, v54
	v_mov_b32_e32 v59, v54
	v_mov_b32_e32 v53, v52
	v_mov_b32_e32 v60, v52
	v_mov_b32_e32 v61, v52
	s_branch .LBB0_548
